# v28 + grid barrier: the XCD leader proceeds without waiting for its local-release atomic to complete
# speedup vs baseline: 1.0027x; 1.0006x over previous
.LBB0_212:
	s_or_b64 exec, exec, s[4:5]
	v_readlane_b32 s4, v253, 50
	v_readlane_b32 s5, v253, 51
	s_waitcnt vmcnt(0)
	s_nop 0
	s_nop 2
	global_atomic_add v64, v216, s[4:5]
	s_nop 0
